# attention tile loop: two row-max ops moved behind the mid-iteration barrier, the s_nop 7 pad in front of it removed
# baseline (speedup 1.0000x reference)
.LBB0_428:
.LBB0_429:
	s_add_i32 s8, s76, 0
	v_add_u32_e32 v90, s8, v207
	v_add_u32_e32 v94, s8, v208
	v_add_u32_e32 v194, s8, v209
	s_waitcnt lgkmcnt(1)
	v_mfma_f32_32x32x16_bf16 v[128:143], v[82:85], v[160:163], v[64:79]
	ds_read_b128 v[82:85], v90
	ds_read_b128 v[90:93], v90 offset:4096
	v_exp_f32_e32 v95, v112
	v_exp_f32_e32 v245, v113
	v_exp_f32_e32 v145, v217
	v_exp_f32_e32 v244, v115
	v_exp_f32_e32 v115, v221
	v_cvt_pk_bf16_f32 v112, v95, v245
	s_waitcnt lgkmcnt(2)
	v_mfma_f32_32x32x16_bf16 v[96:111], v[86:89], v[160:163], v[64:79]
	ds_read_b128 v[86:89], v94
	ds_read_b128 v[232:235], v94 offset:4096
	ds_read_b128 v[236:239], v194
	ds_read_b128 v[240:243], v194 offset:4096
	v_exp_f32_e32 v94, v114
	v_exp_f32_e32 v114, v117
	v_exp_f32_e32 v156, v228
	s_add_i32 s8, s77, s76
	v_cvt_pk_bf16_f32 v113, v94, v244
	s_cmpk_eq_i32 s8, 0x2000
	s_waitcnt lgkmcnt(5)
	v_mfma_f32_32x32x16_bf16 v[128:143], v[82:85], v[164:167], v[128:143]
	v_exp_f32_e32 v85, v216
	v_exp_f32_e32 v84, v218
	v_exp_f32_e32 v144, v219
	s_cselect_b32 s9, s71, 0x2000
	v_cvt_pk_bf16_f32 v82, v85, v145
	s_cmpk_lg_i32 s8, 0x6000
	s_cselect_b32 s76, s9, 0
	s_waitcnt lgkmcnt(4)
	v_mfma_f32_32x32x16_bf16 v[96:111], v[90:93], v[164:167], v[96:111]
	v_add_f32_e32 v90, v94, v244
	v_add_f32_e32 v91, v95, v245
	v_add_f32_e32 v92, v84, v144
	v_add_f32_e32 v93, v85, v145
	v_exp_f32_e32 v94, v120
	v_add_f32_e32 v90, v90, v92
	v_add_f32_e32 v91, v91, v93
	v_exp_f32_e32 v92, v116
	v_exp_f32_e32 v93, v220
	s_waitcnt lgkmcnt(3)
	v_mfma_f32_32x32x16_bf16 v[128:143], v[86:89], v[168:171], v[128:143]
	v_add_f32_e32 v87, v90, v91
	v_cvt_pk_bf16_f32 v83, v84, v144
	v_add_f32_e32 v84, v92, v114
	v_add_f32_e32 v85, v93, v115
	v_exp_f32_e32 v86, v119
	v_add_f32_e32 v89, v84, v85
	v_exp_f32_e32 v85, v118
	v_exp_f32_e32 v88, v222
	v_exp_f32_e32 v90, v223
	s_waitcnt lgkmcnt(2)
	v_mfma_f32_32x32x16_bf16 v[96:111], v[232:235], v[168:171], v[96:111]
	v_cvt_pk_bf16_f32 v114, v92, v114
	v_cvt_pk_bf16_f32 v84, v93, v115
	v_add_f32_e32 v95, v85, v86
	v_add_f32_e32 v233, v88, v90
	v_cvt_pk_bf16_f32 v115, v85, v86
	v_cvt_pk_bf16_f32 v85, v88, v90
	ds_read_b64_tr_b16 v[90:91], v213 offset:24576
	ds_read_b64_tr_b16 v[92:93], v213 offset:26624
	v_exp_f32_e32 v232, v121
	v_exp_f32_e32 v88, v224
	v_exp_f32_e32 v86, v225
	ds_read_b64_tr_b16 v[116:117], v214 offset:24576
	ds_read_b64_tr_b16 v[118:119], v214 offset:26624
	ds_read_b64_tr_b16 v[144:145], v213 offset:28672
	ds_read_b64_tr_b16 v[146:147], v213 offset:30720
	v_add_f32_e32 v120, v94, v232
	v_add_f32_e32 v121, v95, v233
	s_waitcnt lgkmcnt(4)
	v_mfma_f32_32x32x16_bf16 v[48:63], v[90:93], v[112:115], v[48:63]
	v_add_f32_e32 v90, v88, v86
	v_add_f32_e32 v91, v89, v87
	v_exp_f32_e32 v234, v122
	v_add_f32_e32 v152, v120, v90
	v_add_f32_e32 v153, v121, v91
	ds_read_b64_tr_b16 v[90:91], v215 offset:24576
	ds_read_b64_tr_b16 v[92:93], v215 offset:26624
	ds_read_b64_tr_b16 v[148:149], v214 offset:28672
	ds_read_b64_tr_b16 v[150:151], v214 offset:30720
	v_exp_f32_e32 v235, v226
	v_exp_f32_e32 v87, v124
	v_exp_f32_e32 v89, v125
	v_mfma_f32_32x32x16_bf16 v[128:143], v[236:239], v[172:175], v[128:143]
	v_exp_f32_e32 v236, v123
	v_exp_f32_e32 v237, v227
	v_add_f32_e32 v239, v152, v153
	v_exp_f32_e32 v238, v231
	s_min_u32 s8, s4, 32
	s_min_u32 s10, s4, 33
	s_lshl_b32 s8, s8, 17
	s_waitcnt lgkmcnt(6)
	v_mfma_f32_32x32x16_bf16 v[32:47], v[116:119], v[112:115], v[32:47]
	ds_read_b64_tr_b16 v[116:117], v248 offset:24576
	ds_read_b64_tr_b16 v[118:119], v248 offset:26624
	ds_read_b64_tr_b16 v[120:121], v215 offset:28672
	ds_read_b64_tr_b16 v[122:123], v215 offset:30720
	ds_read_b64_tr_b16 v[152:153], v248 offset:28672
	ds_read_b64_tr_b16 v[154:155], v248 offset:30720
	s_add_u32 s8, s36, s8
	s_addc_u32 s9, s37, 0
	s_waitcnt lgkmcnt(8)
	v_mfma_f32_32x32x16_bf16 v[16:31], v[90:93], v[112:115], v[16:31]
	v_add_f32_e32 v92, v234, v236
	v_add_f32_e32 v93, v235, v237
	v_cvt_pk_bf16_f32 v90, v94, v232
	v_add_f32_e32 v95, v92, v93
	v_cvt_pk_bf16_f32 v91, v234, v236
	v_cvt_pk_bf16_f32 v92, v87, v89
	v_exp_f32_e32 v94, v230
	s_waitcnt lgkmcnt(4)
	v_mfma_f32_32x32x16_bf16 v[0:15], v[116:119], v[112:115], v[0:15]
	v_exp_f32_e32 v112, v126
	v_exp_f32_e32 v114, v127
	v_add_f32_e32 v113, v87, v89
	v_cvt_pk_bf16_f32 v93, v112, v114
	s_nop 1
	v_mfma_f32_32x32x16_bf16 v[48:63], v[144:147], v[90:93], v[48:63]
	v_exp_f32_e32 v144, v229
	v_cvt_pk_bf16_f32 v147, v94, v238
	v_cvt_pk_bf16_f32 v145, v235, v237
	v_add_f32_e32 v115, v156, v144
	v_add_f32_e32 v112, v112, v114
	v_add_f32_e32 v113, v113, v115
	v_add_f32_e32 v114, v94, v238
	v_add_f32_e32 v115, v95, v239
	v_mfma_f32_32x32x16_bf16 v[32:47], v[148:151], v[90:93], v[32:47]
	v_add_f32_e32 v112, v112, v114
	v_add_f32_e32 v113, v113, v115
	v_cvt_pk_bf16_f32 v146, v156, v144
	v_add_f32_e32 v87, v112, v113
	ds_read_b64_tr_b16 v[112:113], v213 offset:32768
	ds_read_b64_tr_b16 v[114:115], v213 offset:34816
	v_add_f32_e32 v194, v196, v87
	v_max_f32_e32 v87, v128, v129
	s_waitcnt lgkmcnt(4)
	v_mfma_f32_32x32x16_bf16 v[16:31], v[120:123], v[90:93], v[16:31]
	v_max3_f32 v87, v87, v130, v131
	v_max3_f32 v87, v87, v132, v133
	v_max3_f32 v87, v87, v134, v135
	v_max3_f32 v87, v87, v136, v137
	v_max3_f32 v87, v87, v138, v139
	v_max3_f32 v87, v87, v140, v141
	v_max3_f32 v87, v87, v142, v143
	s_waitcnt lgkmcnt(2)
	v_mfma_f32_32x32x16_bf16 v[0:15], v[152:155], v[90:93], v[0:15]
	ds_read_b64_tr_b16 v[90:91], v214 offset:32768
	ds_read_b64_tr_b16 v[92:93], v214 offset:34816
	ds_read_b64_tr_b16 v[116:117], v213 offset:36864
	ds_read_b64_tr_b16 v[118:119], v213 offset:38912
	v_cvt_pk_bf16_f32 v144, v88, v86
	s_waitcnt lgkmcnt(4)
	v_mfma_f32_32x32x16_bf16 v[48:63], v[112:115], v[82:85], v[48:63]
	ds_read_b64_tr_b16 v[112:113], v215 offset:32768
	ds_read_b64_tr_b16 v[114:115], v215 offset:34816
	ds_read_b64_tr_b16 v[120:121], v214 offset:36864
	ds_read_b64_tr_b16 v[122:123], v214 offset:38912
	s_waitcnt lgkmcnt(6)
	v_mfma_f32_32x32x16_bf16 v[32:47], v[90:93], v[82:85], v[32:47]
	ds_read_b64_tr_b16 v[90:91], v248 offset:32768
	ds_read_b64_tr_b16 v[92:93], v248 offset:34816
	ds_read_b64_tr_b16 v[124:125], v215 offset:36864
	ds_read_b64_tr_b16 v[126:127], v215 offset:38912
	v_mfma_f32_32x32x16_bf16 v[96:111], v[240:243], v[172:175], v[96:111]
	s_waitcnt lgkmcnt(6)
	v_mfma_f32_32x32x16_bf16 v[16:31], v[112:115], v[82:85], v[16:31]
	ds_read_b64_tr_b16 v[112:113], v248 offset:36864
	ds_read_b64_tr_b16 v[114:115], v248 offset:38912
	s_waitcnt vmcnt(0)
	s_waitcnt lgkmcnt(0)
	s_barrier
	v_mfma_f32_32x32x16_bf16 v[0:15], v[90:93], v[82:85], v[0:15]
	s_add_u32 s96, s8, s24
	s_addc_u32 s97, s9, s25
	s_add_i32 m0, s43, s76
	s_nop 0
	global_load_lds_dwordx4 v252, s[96:97]
	s_lshl_b32 s8, s10, 17
	v_max3_f32 v87, v87, v96, v97
	v_max3_f32 v87, v87, v98, v99
	v_max3_f32 v87, v87, v100, v101
	s_add_u32 s8, s26, s8
	v_mfma_f32_32x32x16_bf16 v[48:63], v[116:119], v[144:147], v[48:63]
	v_max3_f32 v87, v87, v102, v103
	s_addc_u32 s9, s27, 0
	v_max3_f32 v87, v87, v104, v105
	s_add_u32 s8, s8, 0x40000
	v_max3_f32 v87, v87, v106, v107
	s_addc_u32 s9, s9, 0
	v_max3_f32 v87, v87, v108, v109
	v_mfma_f32_32x32x16_bf16 v[32:47], v[120:123], v[144:147], v[32:47]
	s_mov_b32 m0, s65
	s_nop 0
	global_load_lds_dwordx4 v253, s[8:9]
	v_max3_f32 v87, v87, v110, v111
	s_mov_b32 m0, s66
	s_nop 0
	global_load_lds_dwordx4 v254, s[8:9]
	v_add_f32_e32 v87, v195, v87
	v_cmp_gt_f32_e32 vcc, v87, v81
	v_mfma_f32_32x32x16_bf16 v[16:31], v[124:127], v[144:147], v[16:31]
	v_mfma_f32_32x32x16_bf16 v[0:15], v[112:115], v[144:147], v[0:15]
	s_cbranch_vccz .LBB0_423
	ds_bpermute_b32 v82, v204, v87
	v_max_f32_e32 v83, v87, v87
	s_waitcnt lgkmcnt(0)
	v_max_f32_e32 v82, v82, v82
	v_max_f32_e32 v112, v83, v82
	v_cmp_gt_f32_e32 vcc, v112, v81
	s_and_saveexec_b64 s[8:9], vcc
	s_cbranch_execz .LBB0_422
	v_sub_f32_e32 v65, v112, v195
	v_exp_f32_e64 v64, -v65
	v_xor_b32_e32 v80, 0x80000000, v112
	v_mov_b32_e32 v81, v80
	v_sub_f32_e32 v128, v128, v65
	v_mul_f32_e32 v194, v194, v64
	v_pk_mul_f32 v[62:63], v[62:63], v[64:65] op_sel_hi:[1,0]
	v_pk_mul_f32 v[60:61], v[60:61], v[64:65] op_sel_hi:[1,0]
	v_pk_mul_f32 v[58:59], v[58:59], v[64:65] op_sel_hi:[1,0]
	v_pk_mul_f32 v[56:57], v[56:57], v[64:65] op_sel_hi:[1,0]
	v_pk_mul_f32 v[54:55], v[54:55], v[64:65] op_sel_hi:[1,0]
	v_pk_mul_f32 v[52:53], v[52:53], v[64:65] op_sel_hi:[1,0]
	v_pk_mul_f32 v[50:51], v[50:51], v[64:65] op_sel_hi:[1,0]
	v_pk_mul_f32 v[48:49], v[48:49], v[64:65] op_sel_hi:[1,0]
	v_pk_mul_f32 v[46:47], v[46:47], v[64:65] op_sel_hi:[1,0]
	v_pk_mul_f32 v[44:45], v[44:45], v[64:65] op_sel_hi:[1,0]
	v_pk_mul_f32 v[42:43], v[42:43], v[64:65] op_sel_hi:[1,0]
	v_pk_mul_f32 v[40:41], v[40:41], v[64:65] op_sel_hi:[1,0]
	v_pk_mul_f32 v[38:39], v[38:39], v[64:65] op_sel_hi:[1,0]
	v_pk_mul_f32 v[36:37], v[36:37], v[64:65] op_sel_hi:[1,0]
	v_pk_mul_f32 v[34:35], v[34:35], v[64:65] op_sel_hi:[1,0]
	v_pk_mul_f32 v[32:33], v[32:33], v[64:65] op_sel_hi:[1,0]
	v_pk_mul_f32 v[30:31], v[30:31], v[64:65] op_sel_hi:[1,0]
	v_pk_mul_f32 v[28:29], v[28:29], v[64:65] op_sel_hi:[1,0]
	v_pk_mul_f32 v[26:27], v[26:27], v[64:65] op_sel_hi:[1,0]
	v_pk_mul_f32 v[24:25], v[24:25], v[64:65] op_sel_hi:[1,0]
	v_pk_mul_f32 v[22:23], v[22:23], v[64:65] op_sel_hi:[1,0]
	v_pk_mul_f32 v[20:21], v[20:21], v[64:65] op_sel_hi:[1,0]
	v_pk_mul_f32 v[18:19], v[18:19], v[64:65] op_sel_hi:[1,0]
	v_pk_mul_f32 v[16:17], v[16:17], v[64:65] op_sel_hi:[1,0]
	v_pk_mul_f32 v[14:15], v[14:15], v[64:65] op_sel_hi:[1,0]
	v_pk_mul_f32 v[12:13], v[12:13], v[64:65] op_sel_hi:[1,0]
	v_pk_mul_f32 v[10:11], v[10:11], v[64:65] op_sel_hi:[1,0]
	v_pk_mul_f32 v[8:9], v[8:9], v[64:65] op_sel_hi:[1,0]
	v_pk_mul_f32 v[6:7], v[6:7], v[64:65] op_sel_hi:[1,0]
	v_pk_mul_f32 v[4:5], v[4:5], v[64:65] op_sel_hi:[1,0]
	v_pk_mul_f32 v[2:3], v[2:3], v[64:65] op_sel_hi:[1,0]
	v_pk_mul_f32 v[0:1], v[0:1], v[64:65] op_sel_hi:[1,0]
	v_sub_f32_e32 v129, v129, v65
	v_sub_f32_e32 v130, v130, v65
	v_sub_f32_e32 v131, v131, v65
	v_sub_f32_e32 v132, v132, v65
	v_sub_f32_e32 v133, v133, v65
	v_sub_f32_e32 v134, v134, v65
	v_sub_f32_e32 v135, v135, v65
	v_sub_f32_e32 v136, v136, v65
	v_sub_f32_e32 v137, v137, v65
	v_sub_f32_e32 v138, v138, v65
	v_sub_f32_e32 v139, v139, v65
	v_sub_f32_e32 v140, v140, v65
	v_sub_f32_e32 v141, v141, v65
	v_sub_f32_e32 v142, v142, v65
	v_sub_f32_e32 v143, v143, v65
	v_sub_f32_e32 v96, v96, v65
	v_sub_f32_e32 v97, v97, v65
	v_sub_f32_e32 v98, v98, v65
	v_sub_f32_e32 v99, v99, v65
	v_sub_f32_e32 v100, v100, v65
	v_sub_f32_e32 v101, v101, v65
	v_sub_f32_e32 v102, v102, v65
	v_sub_f32_e32 v103, v103, v65
	v_sub_f32_e32 v104, v104, v65
	v_sub_f32_e32 v105, v105, v65
	v_sub_f32_e32 v106, v106, v65
	v_sub_f32_e32 v107, v107, v65
	v_sub_f32_e32 v108, v108, v65
	v_sub_f32_e32 v109, v109, v65
	v_sub_f32_e32 v110, v110, v65
	v_sub_f32_e32 v111, v111, v65
	v_mov_b32_e32 v82, v80
	v_mov_b32_e32 v83, v80
	v_mov_b32_e32 v84, v80
	v_mov_b32_e32 v85, v80
	v_mov_b32_e32 v86, v80
	v_mov_b32_e32 v87, v80
	v_mov_b32_e32 v88, v80
	v_mov_b32_e32 v89, v80
	v_mov_b32_e32 v90, v80
	v_mov_b32_e32 v91, v80
	v_mov_b32_e32 v92, v80
	v_mov_b32_e32 v93, v80
	v_mov_b32_e32 v94, v80
	v_mov_b32_e32 v95, v80
	v_mov_b64_e32 v[64:65], v[80:81]
	v_mov_b32_e32 v195, v112
	v_mov_b64_e32 v[66:67], v[82:83]
	v_mov_b64_e32 v[68:69], v[84:85]
	v_mov_b64_e32 v[70:71], v[86:87]
	v_mov_b64_e32 v[72:73], v[88:89]
	v_mov_b64_e32 v[74:75], v[90:91]
	v_mov_b64_e32 v[76:77], v[92:93]
	v_mov_b64_e32 v[78:79], v[94:95]
	s_branch .LBB0_422
